# hand-written fused EpiFfn2 epilogue in P7 (X1 loads batched 16 deep with counted waits, default cache policy, part 2 loads up front)
# speedup vs baseline: 1.0054x; 1.0054x over previous
.LBB0_943:
	s_and_b64 vcc, exec, s[62:63]
	s_cbranch_vccnz .Lp7_orig_epi
	v_lshl_add_u32 v146, s54, 8, v182
	v_lshl_or_b32 v148, s55, 8, v184
	s_ashr_i32 s22, s54, 3
	s_mul_hi_i32 s23, s22, 0xc000
	s_mul_i32 s22, s22, 0xc000
	s_add_u32 s22, s64, s22
	s_addc_u32 s23, s65, s23
	s_add_u32 s22, s22, 0xa000
	s_addc_u32 s23, s23, 0
	v_lshlrev_b32_e32 v149, 2, v148
	v_lshlrev_b32_e32 v150, 2, v146
	v_lshl_add_u32 v147, v146, 13, v149
	v_xor_b32_e32 v151, 16, v188
	v_xor_b32_e32 v152, 32, v188
	v_lshlrev_b32_e32 v151, 2, v151
	v_lshlrev_b32_e32 v152, 2, v152
	global_load_dwordx4 v[160:163], v149, s[22:23] offset:0
	global_load_dwordx4 v[164:167], v149, s[22:23] offset:16
	global_load_dwordx4 v[168:171], v149, s[22:23] offset:512
	global_load_dwordx4 v[172:175], v149, s[22:23] offset:528
	v_mov_b32_e32 v144, v147
	global_load_dwordx4 v[190:193], v144, s[14:15] offset:0
	global_load_dwordx4 v[194:197], v144, s[14:15] offset:16
	global_load_dwordx4 v[198:201], v144, s[14:15] offset:512
	global_load_dwordx4 v[202:205], v144, s[14:15] offset:528
	v_add_u32_e32 v144, 0x20000, v147
	global_load_dwordx4 v[206:209], v144, s[14:15] offset:0
	global_load_dwordx4 v[210:213], v144, s[14:15] offset:16
	global_load_dwordx4 v[214:217], v144, s[14:15] offset:512
	global_load_dwordx4 v[218:221], v144, s[14:15] offset:528
	v_add_u32_e32 v144, 0x40000, v147
	global_load_dwordx4 v[222:225], v144, s[14:15] offset:0
	global_load_dwordx4 v[226:229], v144, s[14:15] offset:16
	global_load_dwordx4 v[230:233], v144, s[14:15] offset:512
	global_load_dwordx4 v[234:237], v144, s[14:15] offset:528
	v_add_u32_e32 v144, 0x60000, v147
	global_load_dwordx4 v[238:241], v144, s[14:15] offset:0
	global_load_dwordx4 v[242:245], v144, s[14:15] offset:16
	global_load_dwordx4 v[246:249], v144, s[14:15] offset:512
	global_load_dwordx4 v[176:179], v144, s[14:15] offset:528
	s_waitcnt vmcnt(12)
	v_pk_fma_f32 v[72:73], v[72:73], v[160:161], v[190:191]
	v_pk_fma_f32 v[74:75], v[74:75], v[162:163], v[192:193]
	v_pk_fma_f32 v[76:77], v[76:77], v[164:165], v[194:195]
	v_pk_fma_f32 v[78:79], v[78:79], v[166:167], v[196:197]
	v_pk_fma_f32 v[80:81], v[80:81], v[168:169], v[198:199]
	v_pk_fma_f32 v[82:83], v[82:83], v[170:171], v[200:201]
	v_pk_fma_f32 v[88:89], v[88:89], v[172:173], v[202:203]
	v_pk_fma_f32 v[90:91], v[90:91], v[174:175], v[204:205]
	v_add_u32_e32 v144, 0x100000, v147
	global_load_dwordx4 v[190:193], v144, s[14:15] offset:0
	global_load_dwordx4 v[194:197], v144, s[14:15] offset:16
	global_load_dwordx4 v[198:201], v144, s[14:15] offset:512
	global_load_dwordx4 v[202:205], v144, s[14:15] offset:528
	v_mul_f32_e32 v154, v73, v73
	v_mul_f32_e32 v158, v75, v75
	v_fmac_f32_e32 v154, v72, v72
	v_fmac_f32_e32 v158, v74, v74
	v_add_f32_e32 v154, v154, v158
	v_mul_f32_e32 v155, v77, v77
	v_mul_f32_e32 v158, v79, v79
	v_fmac_f32_e32 v155, v76, v76
	v_fmac_f32_e32 v158, v78, v78
	v_add_f32_e32 v155, v155, v158
	v_mul_f32_e32 v156, v81, v81
	v_mul_f32_e32 v158, v83, v83
	v_fmac_f32_e32 v156, v80, v80
	v_fmac_f32_e32 v158, v82, v82
	v_add_f32_e32 v156, v156, v158
	v_mul_f32_e32 v157, v89, v89
	v_mul_f32_e32 v158, v91, v91
	v_fmac_f32_e32 v157, v88, v88
	v_fmac_f32_e32 v158, v90, v90
	v_add_f32_e32 v157, v157, v158
	v_add_f32_e32 v154, v154, v155
	v_add_f32_e32 v154, v154, v156
	v_add_f32_e32 v154, v154, v157
	ds_bpermute_b32 v159, v151, v154
	s_waitcnt lgkmcnt(0)
	v_add_f32_e32 v154, v154, v159
	ds_bpermute_b32 v159, v152, v154
	s_waitcnt lgkmcnt(0)
	v_add_f32_e32 v154, v154, v159
	s_and_saveexec_b64 s[24:25], s[40:41]
	global_atomic_add_f32 v150, v154, s[6:7]
	s_or_b64 exec, exec, s[24:25]
	s_waitcnt vmcnt(13)
	v_pk_fma_f32 v[96:97], v[96:97], v[160:161], v[206:207]
	v_pk_fma_f32 v[98:99], v[98:99], v[162:163], v[208:209]
	v_pk_fma_f32 v[100:101], v[100:101], v[164:165], v[210:211]
	v_pk_fma_f32 v[102:103], v[102:103], v[166:167], v[212:213]
	v_pk_fma_f32 v[108:109], v[108:109], v[168:169], v[214:215]
	v_pk_fma_f32 v[110:111], v[110:111], v[170:171], v[216:217]
	v_pk_fma_f32 v[112:113], v[112:113], v[172:173], v[218:219]
	v_pk_fma_f32 v[114:115], v[114:115], v[174:175], v[220:221]
	v_add_u32_e32 v144, 0x120000, v147
	global_load_dwordx4 v[206:209], v144, s[14:15] offset:0
	global_load_dwordx4 v[210:213], v144, s[14:15] offset:16
	global_load_dwordx4 v[214:217], v144, s[14:15] offset:512
	global_load_dwordx4 v[218:221], v144, s[14:15] offset:528
	v_mul_f32_e32 v154, v97, v97
	v_mul_f32_e32 v158, v99, v99
	v_fmac_f32_e32 v154, v96, v96
	v_fmac_f32_e32 v158, v98, v98
	v_add_f32_e32 v154, v154, v158
	v_mul_f32_e32 v155, v101, v101
	v_mul_f32_e32 v158, v103, v103
	v_fmac_f32_e32 v155, v100, v100
	v_fmac_f32_e32 v158, v102, v102
	v_add_f32_e32 v155, v155, v158
	v_mul_f32_e32 v156, v109, v109
	v_mul_f32_e32 v158, v111, v111
	v_fmac_f32_e32 v156, v108, v108
	v_fmac_f32_e32 v158, v110, v110
	v_add_f32_e32 v156, v156, v158
	v_mul_f32_e32 v157, v113, v113
	v_mul_f32_e32 v158, v115, v115
	v_fmac_f32_e32 v157, v112, v112
	v_fmac_f32_e32 v158, v114, v114
	v_add_f32_e32 v157, v157, v158
	v_add_f32_e32 v154, v154, v155
	v_add_f32_e32 v154, v154, v156
	v_add_f32_e32 v154, v154, v157
	ds_bpermute_b32 v159, v151, v154
	s_waitcnt lgkmcnt(0)
	v_add_f32_e32 v154, v154, v159
	ds_bpermute_b32 v159, v152, v154
	s_waitcnt lgkmcnt(0)
	v_add_f32_e32 v154, v154, v159
	s_and_saveexec_b64 s[24:25], s[40:41]
	global_atomic_add_f32 v150, v154, s[6:7] offset:64
	s_or_b64 exec, exec, s[24:25]
	s_waitcnt vmcnt(14)
	v_pk_fma_f32 v[120:121], v[120:121], v[160:161], v[222:223]
	v_pk_fma_f32 v[122:123], v[122:123], v[162:163], v[224:225]
	v_pk_fma_f32 v[124:125], v[124:125], v[164:165], v[226:227]
	v_pk_fma_f32 v[126:127], v[126:127], v[166:167], v[228:229]
	v_pk_fma_f32 v[116:117], v[116:117], v[168:169], v[230:231]
	v_pk_fma_f32 v[118:119], v[118:119], v[170:171], v[232:233]
	v_pk_fma_f32 v[104:105], v[104:105], v[172:173], v[234:235]
	v_pk_fma_f32 v[106:107], v[106:107], v[174:175], v[236:237]
	v_add_u32_e32 v144, 0x140000, v147
	global_load_dwordx4 v[222:225], v144, s[14:15] offset:0
	global_load_dwordx4 v[226:229], v144, s[14:15] offset:16
	global_load_dwordx4 v[230:233], v144, s[14:15] offset:512
	global_load_dwordx4 v[234:237], v144, s[14:15] offset:528
	v_mul_f32_e32 v154, v121, v121
	v_mul_f32_e32 v158, v123, v123
	v_fmac_f32_e32 v154, v120, v120
	v_fmac_f32_e32 v158, v122, v122
	v_add_f32_e32 v154, v154, v158
	v_mul_f32_e32 v155, v125, v125
	v_mul_f32_e32 v158, v127, v127
	v_fmac_f32_e32 v155, v124, v124
	v_fmac_f32_e32 v158, v126, v126
	v_add_f32_e32 v155, v155, v158
	v_mul_f32_e32 v156, v117, v117
	v_mul_f32_e32 v158, v119, v119
	v_fmac_f32_e32 v156, v116, v116
	v_fmac_f32_e32 v158, v118, v118
	v_add_f32_e32 v156, v156, v158
	v_mul_f32_e32 v157, v105, v105
	v_mul_f32_e32 v158, v107, v107
	v_fmac_f32_e32 v157, v104, v104
	v_fmac_f32_e32 v158, v106, v106
	v_add_f32_e32 v157, v157, v158
	v_add_f32_e32 v154, v154, v155
	v_add_f32_e32 v154, v154, v156
	v_add_f32_e32 v154, v154, v157
	ds_bpermute_b32 v159, v151, v154
	s_waitcnt lgkmcnt(0)
	v_add_f32_e32 v154, v154, v159
	ds_bpermute_b32 v159, v152, v154
	s_waitcnt lgkmcnt(0)
	v_add_f32_e32 v154, v154, v159
	s_and_saveexec_b64 s[24:25], s[40:41]
	global_atomic_add_f32 v150, v154, s[6:7] offset:128
	s_or_b64 exec, exec, s[24:25]
	s_waitcnt vmcnt(15)
	v_pk_fma_f32 v[92:93], v[92:93], v[160:161], v[238:239]
	v_pk_fma_f32 v[94:95], v[94:95], v[162:163], v[240:241]
	v_pk_fma_f32 v[84:85], v[84:85], v[164:165], v[242:243]
	v_pk_fma_f32 v[86:87], v[86:87], v[166:167], v[244:245]
	v_pk_fma_f32 v[68:69], v[68:69], v[168:169], v[246:247]
	v_pk_fma_f32 v[70:71], v[70:71], v[170:171], v[248:249]
	v_pk_fma_f32 v[64:65], v[64:65], v[172:173], v[176:177]
	v_pk_fma_f32 v[66:67], v[66:67], v[174:175], v[178:179]
	v_add_u32_e32 v144, 0x160000, v147
	global_load_dwordx4 v[238:241], v144, s[14:15] offset:0
	global_load_dwordx4 v[242:245], v144, s[14:15] offset:16
	global_load_dwordx4 v[246:249], v144, s[14:15] offset:512
	global_load_dwordx4 v[176:179], v144, s[14:15] offset:528
	v_mul_f32_e32 v154, v93, v93
	v_mul_f32_e32 v158, v95, v95
	v_fmac_f32_e32 v154, v92, v92
	v_fmac_f32_e32 v158, v94, v94
	v_add_f32_e32 v154, v154, v158
	v_mul_f32_e32 v155, v85, v85
	v_mul_f32_e32 v158, v87, v87
	v_fmac_f32_e32 v155, v84, v84
	v_fmac_f32_e32 v158, v86, v86
	v_add_f32_e32 v155, v155, v158
	v_mul_f32_e32 v156, v69, v69
	v_mul_f32_e32 v158, v71, v71
	v_fmac_f32_e32 v156, v68, v68
	v_fmac_f32_e32 v158, v70, v70
	v_add_f32_e32 v156, v156, v158
	v_mul_f32_e32 v157, v65, v65
	v_mul_f32_e32 v158, v67, v67
	v_fmac_f32_e32 v157, v64, v64
	v_fmac_f32_e32 v158, v66, v66
	v_add_f32_e32 v157, v157, v158
	v_add_f32_e32 v154, v154, v155
	v_add_f32_e32 v154, v154, v156
	v_add_f32_e32 v154, v154, v157
	ds_bpermute_b32 v159, v151, v154
	s_waitcnt lgkmcnt(0)
	v_add_f32_e32 v154, v154, v159
	ds_bpermute_b32 v159, v152, v154
	s_waitcnt lgkmcnt(0)
	v_add_f32_e32 v154, v154, v159
	s_and_saveexec_b64 s[24:25], s[40:41]
	global_atomic_add_f32 v150, v154, s[6:7] offset:192
	s_or_b64 exec, exec, s[24:25]
	s_waitcnt vmcnt(16)
	v_pk_fma_f32 v[60:61], v[60:61], v[160:161], v[190:191]
	v_pk_fma_f32 v[62:63], v[62:63], v[162:163], v[192:193]
	v_pk_fma_f32 v[56:57], v[56:57], v[164:165], v[194:195]
	v_pk_fma_f32 v[58:59], v[58:59], v[166:167], v[196:197]
	v_pk_fma_f32 v[52:53], v[52:53], v[168:169], v[198:199]
	v_pk_fma_f32 v[54:55], v[54:55], v[170:171], v[200:201]
	v_pk_fma_f32 v[48:49], v[48:49], v[172:173], v[202:203]
	v_pk_fma_f32 v[50:51], v[50:51], v[174:175], v[204:205]
	v_mul_f32_e32 v154, v61, v61
	v_mul_f32_e32 v158, v63, v63
	v_fmac_f32_e32 v154, v60, v60
	v_fmac_f32_e32 v158, v62, v62
	v_add_f32_e32 v154, v154, v158
	v_mul_f32_e32 v155, v57, v57
	v_mul_f32_e32 v158, v59, v59
	v_fmac_f32_e32 v155, v56, v56
	v_fmac_f32_e32 v158, v58, v58
	v_add_f32_e32 v155, v155, v158
	v_mul_f32_e32 v156, v53, v53
	v_mul_f32_e32 v158, v55, v55
	v_fmac_f32_e32 v156, v52, v52
	v_fmac_f32_e32 v158, v54, v54
	v_add_f32_e32 v156, v156, v158
	v_mul_f32_e32 v157, v49, v49
	v_mul_f32_e32 v158, v51, v51
	v_fmac_f32_e32 v157, v48, v48
	v_fmac_f32_e32 v158, v50, v50
	v_add_f32_e32 v157, v157, v158
	v_add_f32_e32 v154, v154, v155
	v_add_f32_e32 v154, v154, v156
	v_add_f32_e32 v154, v154, v157
	ds_bpermute_b32 v159, v151, v154
	s_waitcnt lgkmcnt(0)
	v_add_f32_e32 v154, v154, v159
	ds_bpermute_b32 v159, v152, v154
	s_waitcnt lgkmcnt(0)
	v_add_f32_e32 v154, v154, v159
	s_and_saveexec_b64 s[24:25], s[40:41]
	global_atomic_add_f32 v150, v154, s[6:7] offset:512
	s_or_b64 exec, exec, s[24:25]
	s_waitcnt vmcnt(12)
	v_pk_fma_f32 v[44:45], v[44:45], v[160:161], v[206:207]
	v_pk_fma_f32 v[46:47], v[46:47], v[162:163], v[208:209]
	v_pk_fma_f32 v[40:41], v[40:41], v[164:165], v[210:211]
	v_pk_fma_f32 v[42:43], v[42:43], v[166:167], v[212:213]
	v_pk_fma_f32 v[36:37], v[36:37], v[168:169], v[214:215]
	v_pk_fma_f32 v[38:39], v[38:39], v[170:171], v[216:217]
	v_pk_fma_f32 v[32:33], v[32:33], v[172:173], v[218:219]
	v_pk_fma_f32 v[34:35], v[34:35], v[174:175], v[220:221]
	v_mul_f32_e32 v154, v45, v45
	v_mul_f32_e32 v158, v47, v47
	v_fmac_f32_e32 v154, v44, v44
	v_fmac_f32_e32 v158, v46, v46
	v_add_f32_e32 v154, v154, v158
	v_mul_f32_e32 v155, v41, v41
	v_mul_f32_e32 v158, v43, v43
	v_fmac_f32_e32 v155, v40, v40
	v_fmac_f32_e32 v158, v42, v42
	v_add_f32_e32 v155, v155, v158
	v_mul_f32_e32 v156, v37, v37
	v_mul_f32_e32 v158, v39, v39
	v_fmac_f32_e32 v156, v36, v36
	v_fmac_f32_e32 v158, v38, v38
	v_add_f32_e32 v156, v156, v158
	v_mul_f32_e32 v157, v33, v33
	v_mul_f32_e32 v158, v35, v35
	v_fmac_f32_e32 v157, v32, v32
	v_fmac_f32_e32 v158, v34, v34
	v_add_f32_e32 v157, v157, v158
	v_add_f32_e32 v154, v154, v155
	v_add_f32_e32 v154, v154, v156
	v_add_f32_e32 v154, v154, v157
	ds_bpermute_b32 v159, v151, v154
	s_waitcnt lgkmcnt(0)
	v_add_f32_e32 v154, v154, v159
	ds_bpermute_b32 v159, v152, v154
	s_waitcnt lgkmcnt(0)
	v_add_f32_e32 v154, v154, v159
	s_and_saveexec_b64 s[24:25], s[40:41]
	global_atomic_add_f32 v150, v154, s[6:7] offset:576
	s_or_b64 exec, exec, s[24:25]
	s_waitcnt vmcnt(8)
	v_pk_fma_f32 v[28:29], v[28:29], v[160:161], v[222:223]
	v_pk_fma_f32 v[30:31], v[30:31], v[162:163], v[224:225]
	v_pk_fma_f32 v[24:25], v[24:25], v[164:165], v[226:227]
	v_pk_fma_f32 v[26:27], v[26:27], v[166:167], v[228:229]
	v_pk_fma_f32 v[20:21], v[20:21], v[168:169], v[230:231]
	v_pk_fma_f32 v[22:23], v[22:23], v[170:171], v[232:233]
	v_pk_fma_f32 v[16:17], v[16:17], v[172:173], v[234:235]
	v_pk_fma_f32 v[18:19], v[18:19], v[174:175], v[236:237]
	v_mul_f32_e32 v154, v29, v29
	v_mul_f32_e32 v158, v31, v31
	v_fmac_f32_e32 v154, v28, v28
	v_fmac_f32_e32 v158, v30, v30
	v_add_f32_e32 v154, v154, v158
	v_mul_f32_e32 v155, v25, v25
	v_mul_f32_e32 v158, v27, v27
	v_fmac_f32_e32 v155, v24, v24
	v_fmac_f32_e32 v158, v26, v26
	v_add_f32_e32 v155, v155, v158
	v_mul_f32_e32 v156, v21, v21
	v_mul_f32_e32 v158, v23, v23
	v_fmac_f32_e32 v156, v20, v20
	v_fmac_f32_e32 v158, v22, v22
	v_add_f32_e32 v156, v156, v158
	v_mul_f32_e32 v157, v17, v17
	v_mul_f32_e32 v158, v19, v19
	v_fmac_f32_e32 v157, v16, v16
	v_fmac_f32_e32 v158, v18, v18
	v_add_f32_e32 v157, v157, v158
	v_add_f32_e32 v154, v154, v155
	v_add_f32_e32 v154, v154, v156
	v_add_f32_e32 v154, v154, v157
	ds_bpermute_b32 v159, v151, v154
	s_waitcnt lgkmcnt(0)
	v_add_f32_e32 v154, v154, v159
	ds_bpermute_b32 v159, v152, v154
	s_waitcnt lgkmcnt(0)
	v_add_f32_e32 v154, v154, v159
	s_and_saveexec_b64 s[24:25], s[40:41]
	global_atomic_add_f32 v150, v154, s[6:7] offset:640
	s_or_b64 exec, exec, s[24:25]
	s_waitcnt vmcnt(4)
	v_pk_fma_f32 v[12:13], v[12:13], v[160:161], v[238:239]
	v_pk_fma_f32 v[14:15], v[14:15], v[162:163], v[240:241]
	v_pk_fma_f32 v[8:9], v[8:9], v[164:165], v[242:243]
	v_pk_fma_f32 v[10:11], v[10:11], v[166:167], v[244:245]
	v_pk_fma_f32 v[4:5], v[4:5], v[168:169], v[246:247]
	v_pk_fma_f32 v[6:7], v[6:7], v[170:171], v[248:249]
	v_pk_fma_f32 v[0:1], v[0:1], v[172:173], v[176:177]
	v_pk_fma_f32 v[2:3], v[2:3], v[174:175], v[178:179]
	v_mul_f32_e32 v154, v13, v13
	v_mul_f32_e32 v158, v15, v15
	v_fmac_f32_e32 v154, v12, v12
	v_fmac_f32_e32 v158, v14, v14
	v_add_f32_e32 v154, v154, v158
	v_mul_f32_e32 v155, v9, v9
	v_mul_f32_e32 v158, v11, v11
	v_fmac_f32_e32 v155, v8, v8
	v_fmac_f32_e32 v158, v10, v10
	v_add_f32_e32 v155, v155, v158
	v_mul_f32_e32 v156, v5, v5
	v_mul_f32_e32 v158, v7, v7
	v_fmac_f32_e32 v156, v4, v4
	v_fmac_f32_e32 v158, v6, v6
	v_add_f32_e32 v156, v156, v158
	v_mul_f32_e32 v157, v1, v1
	v_mul_f32_e32 v158, v3, v3
	v_fmac_f32_e32 v157, v0, v0
	v_fmac_f32_e32 v158, v2, v2
	v_add_f32_e32 v157, v157, v158
	v_add_f32_e32 v154, v154, v155
	v_add_f32_e32 v154, v154, v156
	v_add_f32_e32 v154, v154, v157
	ds_bpermute_b32 v159, v151, v154
	s_waitcnt lgkmcnt(0)
	v_add_f32_e32 v154, v154, v159
	ds_bpermute_b32 v159, v152, v154
	s_waitcnt lgkmcnt(0)
	v_add_f32_e32 v154, v154, v159
	s_and_saveexec_b64 s[24:25], s[40:41]
	global_atomic_add_f32 v150, v154, s[6:7] offset:704
	s_or_b64 exec, exec, s[24:25]
	s_lshl_b32 s22, s54, 6
	s_ashr_i32 s23, s22, 31
	s_waitcnt vmcnt(0)
	s_lshl_b64 s[22:23], s[22:23], 2
	s_add_u32 s22, s37, s22
	s_addc_u32 s23, s42, s23
	s_and_saveexec_b64 s[24:25], s[0:1]
	s_cbranch_execz .Lp7_c1028
	s_mov_b64 s[26:27], exec
	v_mbcnt_lo_u32_b32 v154, s26, 0
	v_mbcnt_hi_u32_b32 v154, s27, v154
	v_cmp_eq_u32_e32 vcc, 0, v154
	s_and_b64 s[28:29], exec, vcc
	s_mov_b64 exec, s[28:29]
	s_cbranch_execz .Lp7_c1028
	s_bcnt1_i32_b64 s26, s[26:27]
	v_mov_b32_e32 v154, s26
	global_atomic_add v131, v154, s[22:23]

.Lp7_c1033:
	s_or_b64 exec, exec, s[24:25]
	s_waitcnt vmcnt(0) lgkmcnt(0)
	s_nop 0
	s_barrier
	global_load_dword v190, v150, s[6:7] sc1
	global_load_dword v191, v150, s[6:7] offset:64 sc1
	global_load_dword v192, v150, s[6:7] offset:128 sc1
	global_load_dword v193, v150, s[6:7] offset:192 sc1
	global_load_dword v194, v150, s[6:7] offset:512 sc1
	global_load_dword v195, v150, s[6:7] offset:576 sc1
	global_load_dword v196, v150, s[6:7] offset:640 sc1
	global_load_dword v197, v150, s[6:7] offset:704 sc1
	global_load_dwordx4 v[198:201], v149, s[88:89] offset:0
	global_load_dwordx4 v[202:205], v149, s[88:89] offset:16
	global_load_dwordx4 v[206:209], v149, s[88:89] offset:512
	global_load_dwordx4 v[210:213], v149, s[88:89] offset:528
	s_waitcnt vmcnt(0)
	v_fmamk_f32 v214, v190, 0x3a000000, v189
	v_rsq_f32_e32 v214, v214
	s_nop 0
	v_pk_mul_f32 v[72:73], v[72:73], v[214:215] op_sel_hi:[1,0]
	v_pk_mul_f32 v[74:75], v[74:75], v[214:215] op_sel_hi:[1,0]
	v_pk_mul_f32 v[72:73], v[198:199], v[72:73]
	v_pk_mul_f32 v[74:75], v[200:201], v[74:75]
	v_pk_mul_f32 v[76:77], v[76:77], v[214:215] op_sel_hi:[1,0]
	v_pk_mul_f32 v[78:79], v[78:79], v[214:215] op_sel_hi:[1,0]
	v_pk_mul_f32 v[76:77], v[202:203], v[76:77]
	v_pk_mul_f32 v[78:79], v[204:205], v[78:79]
	v_pk_mul_f32 v[80:81], v[80:81], v[214:215] op_sel_hi:[1,0]
	v_pk_mul_f32 v[82:83], v[82:83], v[214:215] op_sel_hi:[1,0]
	v_pk_mul_f32 v[80:81], v[206:207], v[80:81]
	v_pk_mul_f32 v[82:83], v[208:209], v[82:83]
	v_pk_mul_f32 v[88:89], v[88:89], v[214:215] op_sel_hi:[1,0]
	v_pk_mul_f32 v[90:91], v[90:91], v[214:215] op_sel_hi:[1,0]
	v_pk_mul_f32 v[88:89], v[210:211], v[88:89]
	v_pk_mul_f32 v[90:91], v[212:213], v[90:91]
	v_mov_b32_e32 v144, v147
	global_store_dwordx4 v144, v[72:75], s[90:91] offset:0
	global_store_dwordx4 v144, v[76:79], s[90:91] offset:16
	global_store_dwordx4 v144, v[80:83], s[90:91] offset:512
	global_store_dwordx4 v144, v[88:91], s[90:91] offset:528
	v_fmamk_f32 v214, v191, 0x3a000000, v189
	v_rsq_f32_e32 v214, v214
	s_nop 0
	v_pk_mul_f32 v[96:97], v[96:97], v[214:215] op_sel_hi:[1,0]
	v_pk_mul_f32 v[98:99], v[98:99], v[214:215] op_sel_hi:[1,0]
	v_pk_mul_f32 v[96:97], v[198:199], v[96:97]
	v_pk_mul_f32 v[98:99], v[200:201], v[98:99]
	v_pk_mul_f32 v[100:101], v[100:101], v[214:215] op_sel_hi:[1,0]
	v_pk_mul_f32 v[102:103], v[102:103], v[214:215] op_sel_hi:[1,0]
	v_pk_mul_f32 v[100:101], v[202:203], v[100:101]
	v_pk_mul_f32 v[102:103], v[204:205], v[102:103]
	v_pk_mul_f32 v[108:109], v[108:109], v[214:215] op_sel_hi:[1,0]
	v_pk_mul_f32 v[110:111], v[110:111], v[214:215] op_sel_hi:[1,0]
	v_pk_mul_f32 v[108:109], v[206:207], v[108:109]
	v_pk_mul_f32 v[110:111], v[208:209], v[110:111]
	v_pk_mul_f32 v[112:113], v[112:113], v[214:215] op_sel_hi:[1,0]
	v_pk_mul_f32 v[114:115], v[114:115], v[214:215] op_sel_hi:[1,0]
	v_pk_mul_f32 v[112:113], v[210:211], v[112:113]
	v_pk_mul_f32 v[114:115], v[212:213], v[114:115]
	v_add_u32_e32 v144, 0x20000, v147
	global_store_dwordx4 v144, v[96:99], s[90:91] offset:0
	global_store_dwordx4 v144, v[100:103], s[90:91] offset:16
	global_store_dwordx4 v144, v[108:111], s[90:91] offset:512
	global_store_dwordx4 v144, v[112:115], s[90:91] offset:528
	v_fmamk_f32 v214, v192, 0x3a000000, v189
	v_rsq_f32_e32 v214, v214
	s_nop 0
	v_pk_mul_f32 v[120:121], v[120:121], v[214:215] op_sel_hi:[1,0]
	v_pk_mul_f32 v[122:123], v[122:123], v[214:215] op_sel_hi:[1,0]
	v_pk_mul_f32 v[120:121], v[198:199], v[120:121]
	v_pk_mul_f32 v[122:123], v[200:201], v[122:123]
	v_pk_mul_f32 v[124:125], v[124:125], v[214:215] op_sel_hi:[1,0]
	v_pk_mul_f32 v[126:127], v[126:127], v[214:215] op_sel_hi:[1,0]
	v_pk_mul_f32 v[124:125], v[202:203], v[124:125]
	v_pk_mul_f32 v[126:127], v[204:205], v[126:127]
	v_pk_mul_f32 v[116:117], v[116:117], v[214:215] op_sel_hi:[1,0]
	v_pk_mul_f32 v[118:119], v[118:119], v[214:215] op_sel_hi:[1,0]
	v_pk_mul_f32 v[116:117], v[206:207], v[116:117]
	v_pk_mul_f32 v[118:119], v[208:209], v[118:119]
	v_pk_mul_f32 v[104:105], v[104:105], v[214:215] op_sel_hi:[1,0]
	v_pk_mul_f32 v[106:107], v[106:107], v[214:215] op_sel_hi:[1,0]
	v_pk_mul_f32 v[104:105], v[210:211], v[104:105]
	v_pk_mul_f32 v[106:107], v[212:213], v[106:107]
	v_add_u32_e32 v144, 0x40000, v147
	global_store_dwordx4 v144, v[120:123], s[90:91] offset:0
	global_store_dwordx4 v144, v[124:127], s[90:91] offset:16
	global_store_dwordx4 v144, v[116:119], s[90:91] offset:512
	global_store_dwordx4 v144, v[104:107], s[90:91] offset:528
	v_fmamk_f32 v214, v193, 0x3a000000, v189
	v_rsq_f32_e32 v214, v214
	s_nop 0
	v_pk_mul_f32 v[92:93], v[92:93], v[214:215] op_sel_hi:[1,0]
	v_pk_mul_f32 v[94:95], v[94:95], v[214:215] op_sel_hi:[1,0]
	v_pk_mul_f32 v[92:93], v[198:199], v[92:93]
	v_pk_mul_f32 v[94:95], v[200:201], v[94:95]
	v_pk_mul_f32 v[84:85], v[84:85], v[214:215] op_sel_hi:[1,0]
	v_pk_mul_f32 v[86:87], v[86:87], v[214:215] op_sel_hi:[1,0]
	v_pk_mul_f32 v[84:85], v[202:203], v[84:85]
	v_pk_mul_f32 v[86:87], v[204:205], v[86:87]
	v_pk_mul_f32 v[68:69], v[68:69], v[214:215] op_sel_hi:[1,0]
	v_pk_mul_f32 v[70:71], v[70:71], v[214:215] op_sel_hi:[1,0]
	v_pk_mul_f32 v[68:69], v[206:207], v[68:69]
	v_pk_mul_f32 v[70:71], v[208:209], v[70:71]
	v_pk_mul_f32 v[64:65], v[64:65], v[214:215] op_sel_hi:[1,0]
	v_pk_mul_f32 v[66:67], v[66:67], v[214:215] op_sel_hi:[1,0]
	v_pk_mul_f32 v[64:65], v[210:211], v[64:65]
	v_pk_mul_f32 v[66:67], v[212:213], v[66:67]
	v_add_u32_e32 v144, 0x60000, v147
	global_store_dwordx4 v144, v[92:95], s[90:91] offset:0
	global_store_dwordx4 v144, v[84:87], s[90:91] offset:16
	global_store_dwordx4 v144, v[68:71], s[90:91] offset:512
	global_store_dwordx4 v144, v[64:67], s[90:91] offset:528
	v_fmamk_f32 v214, v194, 0x3a000000, v189
	v_rsq_f32_e32 v214, v214
	s_nop 0
	v_pk_mul_f32 v[60:61], v[60:61], v[214:215] op_sel_hi:[1,0]
	v_pk_mul_f32 v[62:63], v[62:63], v[214:215] op_sel_hi:[1,0]
	v_pk_mul_f32 v[60:61], v[198:199], v[60:61]
	v_pk_mul_f32 v[62:63], v[200:201], v[62:63]
	v_pk_mul_f32 v[56:57], v[56:57], v[214:215] op_sel_hi:[1,0]
	v_pk_mul_f32 v[58:59], v[58:59], v[214:215] op_sel_hi:[1,0]
	v_pk_mul_f32 v[56:57], v[202:203], v[56:57]
	v_pk_mul_f32 v[58:59], v[204:205], v[58:59]
	v_pk_mul_f32 v[52:53], v[52:53], v[214:215] op_sel_hi:[1,0]
	v_pk_mul_f32 v[54:55], v[54:55], v[214:215] op_sel_hi:[1,0]
	v_pk_mul_f32 v[52:53], v[206:207], v[52:53]
	v_pk_mul_f32 v[54:55], v[208:209], v[54:55]
	v_pk_mul_f32 v[48:49], v[48:49], v[214:215] op_sel_hi:[1,0]
	v_pk_mul_f32 v[50:51], v[50:51], v[214:215] op_sel_hi:[1,0]
	v_pk_mul_f32 v[48:49], v[210:211], v[48:49]
	v_pk_mul_f32 v[50:51], v[212:213], v[50:51]
	v_add_u32_e32 v144, 0x100000, v147
	global_store_dwordx4 v144, v[60:63], s[90:91] offset:0
	global_store_dwordx4 v144, v[56:59], s[90:91] offset:16
	global_store_dwordx4 v144, v[52:55], s[90:91] offset:512
	global_store_dwordx4 v144, v[48:51], s[90:91] offset:528
	v_fmamk_f32 v214, v195, 0x3a000000, v189
	v_rsq_f32_e32 v214, v214
	s_nop 0
	v_pk_mul_f32 v[44:45], v[44:45], v[214:215] op_sel_hi:[1,0]
	v_pk_mul_f32 v[46:47], v[46:47], v[214:215] op_sel_hi:[1,0]
	v_pk_mul_f32 v[44:45], v[198:199], v[44:45]
	v_pk_mul_f32 v[46:47], v[200:201], v[46:47]
	v_pk_mul_f32 v[40:41], v[40:41], v[214:215] op_sel_hi:[1,0]
	v_pk_mul_f32 v[42:43], v[42:43], v[214:215] op_sel_hi:[1,0]
	v_pk_mul_f32 v[40:41], v[202:203], v[40:41]
	v_pk_mul_f32 v[42:43], v[204:205], v[42:43]
	v_pk_mul_f32 v[36:37], v[36:37], v[214:215] op_sel_hi:[1,0]
	v_pk_mul_f32 v[38:39], v[38:39], v[214:215] op_sel_hi:[1,0]
	v_pk_mul_f32 v[36:37], v[206:207], v[36:37]
	v_pk_mul_f32 v[38:39], v[208:209], v[38:39]
	v_pk_mul_f32 v[32:33], v[32:33], v[214:215] op_sel_hi:[1,0]
	v_pk_mul_f32 v[34:35], v[34:35], v[214:215] op_sel_hi:[1,0]
	v_pk_mul_f32 v[32:33], v[210:211], v[32:33]
	v_pk_mul_f32 v[34:35], v[212:213], v[34:35]
	v_add_u32_e32 v144, 0x120000, v147
	global_store_dwordx4 v144, v[44:47], s[90:91] offset:0
	global_store_dwordx4 v144, v[40:43], s[90:91] offset:16
	global_store_dwordx4 v144, v[36:39], s[90:91] offset:512
	global_store_dwordx4 v144, v[32:35], s[90:91] offset:528
	v_fmamk_f32 v214, v196, 0x3a000000, v189
	v_rsq_f32_e32 v214, v214
	s_nop 0
	v_pk_mul_f32 v[28:29], v[28:29], v[214:215] op_sel_hi:[1,0]
	v_pk_mul_f32 v[30:31], v[30:31], v[214:215] op_sel_hi:[1,0]
	v_pk_mul_f32 v[28:29], v[198:199], v[28:29]
	v_pk_mul_f32 v[30:31], v[200:201], v[30:31]
	v_pk_mul_f32 v[24:25], v[24:25], v[214:215] op_sel_hi:[1,0]
	v_pk_mul_f32 v[26:27], v[26:27], v[214:215] op_sel_hi:[1,0]
	v_pk_mul_f32 v[24:25], v[202:203], v[24:25]
	v_pk_mul_f32 v[26:27], v[204:205], v[26:27]
	v_pk_mul_f32 v[20:21], v[20:21], v[214:215] op_sel_hi:[1,0]
	v_pk_mul_f32 v[22:23], v[22:23], v[214:215] op_sel_hi:[1,0]
	v_pk_mul_f32 v[20:21], v[206:207], v[20:21]
	v_pk_mul_f32 v[22:23], v[208:209], v[22:23]
	v_pk_mul_f32 v[16:17], v[16:17], v[214:215] op_sel_hi:[1,0]
	v_pk_mul_f32 v[18:19], v[18:19], v[214:215] op_sel_hi:[1,0]
	v_pk_mul_f32 v[16:17], v[210:211], v[16:17]
	v_pk_mul_f32 v[18:19], v[212:213], v[18:19]
	v_add_u32_e32 v144, 0x140000, v147
	global_store_dwordx4 v144, v[28:31], s[90:91] offset:0
	global_store_dwordx4 v144, v[24:27], s[90:91] offset:16
	global_store_dwordx4 v144, v[20:23], s[90:91] offset:512
	global_store_dwordx4 v144, v[16:19], s[90:91] offset:528
	v_fmamk_f32 v214, v197, 0x3a000000, v189
	v_rsq_f32_e32 v214, v214
	s_nop 0
	v_pk_mul_f32 v[12:13], v[12:13], v[214:215] op_sel_hi:[1,0]
	v_pk_mul_f32 v[14:15], v[14:15], v[214:215] op_sel_hi:[1,0]
	v_pk_mul_f32 v[12:13], v[198:199], v[12:13]
	v_pk_mul_f32 v[14:15], v[200:201], v[14:15]
	v_pk_mul_f32 v[8:9], v[8:9], v[214:215] op_sel_hi:[1,0]
	v_pk_mul_f32 v[10:11], v[10:11], v[214:215] op_sel_hi:[1,0]
	v_pk_mul_f32 v[8:9], v[202:203], v[8:9]
	v_pk_mul_f32 v[10:11], v[204:205], v[10:11]
	v_pk_mul_f32 v[4:5], v[4:5], v[214:215] op_sel_hi:[1,0]
	v_pk_mul_f32 v[6:7], v[6:7], v[214:215] op_sel_hi:[1,0]
	v_pk_mul_f32 v[4:5], v[206:207], v[4:5]
	v_pk_mul_f32 v[6:7], v[208:209], v[6:7]
	v_pk_mul_f32 v[0:1], v[0:1], v[214:215] op_sel_hi:[1,0]
	v_pk_mul_f32 v[2:3], v[2:3], v[214:215] op_sel_hi:[1,0]
	v_pk_mul_f32 v[0:1], v[210:211], v[0:1]
	v_pk_mul_f32 v[2:3], v[212:213], v[2:3]
	v_add_u32_e32 v144, 0x160000, v147
	global_store_dwordx4 v144, v[12:15], s[90:91] offset:0
	global_store_dwordx4 v144, v[8:11], s[90:91] offset:16
	global_store_dwordx4 v144, v[4:7], s[90:91] offset:512
	global_store_dwordx4 v144, v[0:3], s[90:91] offset:528
	s_branch .Lp7_epi_tail

.LBB0_1033:
	s_or_b64 exec, exec, s[24:25]
	s_waitcnt vmcnt(0) lgkmcnt(0)
	s_nop 0
	s_barrier
	global_load_dword v156, v[144:145], off sc1
	v_lshlrev_b64 v[154:155], 2, v[148:149]
	v_lshl_add_u64 v[148:149], s[88:89], 0, v[154:155]
	global_load_dwordx4 v[176:179], v[148:149], off
	v_lshlrev_b64 v[146:147], 13, v[146:147]
	v_lshl_add_u64 v[146:147], s[90:91], 0, v[146:147]
	v_lshl_add_u64 v[146:147], v[146:147], 0, v[154:155]
	s_waitcnt vmcnt(1)
	v_fmamk_f32 v156, v156, 0x3a000000, v189
	v_rsq_f32_e32 v156, v156
	s_nop 0
	v_pk_mul_f32 v[72:73], v[72:73], v[156:157] op_sel_hi:[1,0]
	v_pk_mul_f32 v[74:75], v[74:75], v[156:157] op_sel_hi:[1,0]
	s_waitcnt vmcnt(0)
	v_pk_mul_f32 v[72:73], v[176:177], v[72:73]
	v_pk_mul_f32 v[74:75], v[178:179], v[74:75]
	global_store_dwordx4 v[146:147], v[72:75], off
	global_load_dwordx4 v[72:75], v[148:149], off offset:16
	v_pk_mul_f32 v[76:77], v[76:77], v[156:157] op_sel_hi:[1,0]
	v_pk_mul_f32 v[78:79], v[78:79], v[156:157] op_sel_hi:[1,0]
	s_waitcnt vmcnt(0)
	v_pk_mul_f32 v[72:73], v[72:73], v[76:77]
	v_pk_mul_f32 v[74:75], v[74:75], v[78:79]
	global_store_dwordx4 v[146:147], v[72:75], off offset:16
	global_load_dwordx4 v[72:75], v[148:149], off offset:512
	v_pk_mul_f32 v[76:77], v[80:81], v[156:157] op_sel_hi:[1,0]
	v_pk_mul_f32 v[78:79], v[82:83], v[156:157] op_sel_hi:[1,0]
	s_waitcnt vmcnt(0)
	v_pk_mul_f32 v[72:73], v[72:73], v[76:77]
	v_pk_mul_f32 v[74:75], v[74:75], v[78:79]
	global_store_dwordx4 v[146:147], v[72:75], off offset:512
	global_load_dwordx4 v[72:75], v[148:149], off offset:528
	v_pk_mul_f32 v[76:77], v[88:89], v[156:157] op_sel_hi:[1,0]
	v_pk_mul_f32 v[78:79], v[90:91], v[156:157] op_sel_hi:[1,0]
	s_waitcnt vmcnt(0)
	v_pk_mul_f32 v[72:73], v[76:77], v[72:73]
	v_pk_mul_f32 v[74:75], v[78:79], v[74:75]
	global_store_dwordx4 v[146:147], v[72:75], off offset:528
	global_load_dword v76, v[160:161], off sc1
	s_nop 0
	global_load_dwordx4 v[72:75], v[148:149], off
	v_lshlrev_b64 v[78:79], 13, v[150:151]
	v_lshl_add_u64 v[78:79], s[90:91], 0, v[78:79]
	v_lshl_add_u64 v[78:79], v[78:79], 0, v[154:155]
	s_waitcnt vmcnt(1)
	v_fmamk_f32 v76, v76, 0x3a000000, v189
	v_rsq_f32_e32 v76, v76
	s_nop 0
	v_pk_mul_f32 v[80:81], v[96:97], v[76:77] op_sel_hi:[1,0]
	v_pk_mul_f32 v[82:83], v[98:99], v[76:77] op_sel_hi:[1,0]
	s_waitcnt vmcnt(0)
	v_pk_mul_f32 v[72:73], v[72:73], v[80:81]
	v_pk_mul_f32 v[74:75], v[74:75], v[82:83]
	global_store_dwordx4 v[78:79], v[72:75], off
	global_load_dwordx4 v[72:75], v[148:149], off offset:16
	v_pk_mul_f32 v[80:81], v[100:101], v[76:77] op_sel_hi:[1,0]
	v_pk_mul_f32 v[82:83], v[102:103], v[76:77] op_sel_hi:[1,0]
	s_waitcnt vmcnt(0)
	v_pk_mul_f32 v[72:73], v[72:73], v[80:81]
	v_pk_mul_f32 v[74:75], v[74:75], v[82:83]
	global_store_dwordx4 v[78:79], v[72:75], off offset:16
	global_load_dwordx4 v[72:75], v[148:149], off offset:512
	v_pk_mul_f32 v[80:81], v[108:109], v[76:77] op_sel_hi:[1,0]
	v_pk_mul_f32 v[82:83], v[110:111], v[76:77] op_sel_hi:[1,0]
	s_waitcnt vmcnt(0)
	v_pk_mul_f32 v[72:73], v[72:73], v[80:81]
	v_pk_mul_f32 v[74:75], v[74:75], v[82:83]
	global_store_dwordx4 v[78:79], v[72:75], off offset:512
	global_load_dwordx4 v[72:75], v[148:149], off offset:528
	v_pk_mul_f32 v[80:81], v[112:113], v[76:77] op_sel_hi:[1,0]
	v_pk_mul_f32 v[76:77], v[114:115], v[76:77] op_sel_hi:[1,0]
	s_waitcnt vmcnt(0)
	v_pk_mul_f32 v[72:73], v[80:81], v[72:73]
	v_pk_mul_f32 v[74:75], v[76:77], v[74:75]
	global_store_dwordx4 v[78:79], v[72:75], off offset:528
	global_load_dword v76, v[166:167], off sc1
	s_nop 0
	global_load_dwordx4 v[72:75], v[148:149], off
	v_lshlrev_b64 v[78:79], 13, v[152:153]
	v_lshl_add_u64 v[78:79], s[90:91], 0, v[78:79]
	v_lshl_add_u64 v[78:79], v[78:79], 0, v[154:155]
	s_waitcnt vmcnt(1)
	v_fmamk_f32 v76, v76, 0x3a000000, v189
	v_rsq_f32_e32 v76, v76
	s_nop 0
	v_pk_mul_f32 v[80:81], v[120:121], v[76:77] op_sel_hi:[1,0]
	v_pk_mul_f32 v[82:83], v[122:123], v[76:77] op_sel_hi:[1,0]
	s_waitcnt vmcnt(0)
	v_pk_mul_f32 v[72:73], v[72:73], v[80:81]
	v_pk_mul_f32 v[74:75], v[74:75], v[82:83]
	global_store_dwordx4 v[78:79], v[72:75], off
	global_load_dwordx4 v[72:75], v[148:149], off offset:16
	v_pk_mul_f32 v[80:81], v[124:125], v[76:77] op_sel_hi:[1,0]
	v_pk_mul_f32 v[82:83], v[126:127], v[76:77] op_sel_hi:[1,0]
	s_waitcnt vmcnt(0)
	v_pk_mul_f32 v[72:73], v[72:73], v[80:81]
	v_pk_mul_f32 v[74:75], v[74:75], v[82:83]
	global_store_dwordx4 v[78:79], v[72:75], off offset:16
	global_load_dwordx4 v[72:75], v[148:149], off offset:512
	v_pk_mul_f32 v[80:81], v[116:117], v[76:77] op_sel_hi:[1,0]
	v_pk_mul_f32 v[82:83], v[118:119], v[76:77] op_sel_hi:[1,0]
	s_waitcnt vmcnt(0)
	v_pk_mul_f32 v[72:73], v[72:73], v[80:81]
	v_pk_mul_f32 v[74:75], v[74:75], v[82:83]
	global_store_dwordx4 v[78:79], v[72:75], off offset:512
	global_load_dwordx4 v[72:75], v[148:149], off offset:528
	v_pk_mul_f32 v[80:81], v[104:105], v[76:77] op_sel_hi:[1,0]
	v_pk_mul_f32 v[76:77], v[106:107], v[76:77] op_sel_hi:[1,0]
	s_waitcnt vmcnt(0)
	v_pk_mul_f32 v[72:73], v[80:81], v[72:73]
	v_pk_mul_f32 v[74:75], v[76:77], v[74:75]
	global_store_dwordx4 v[78:79], v[72:75], off offset:528
	global_load_dword v76, v[170:171], off sc1
	s_nop 0
	global_load_dwordx4 v[72:75], v[148:149], off
	v_lshlrev_b64 v[78:79], 13, v[158:159]
	v_lshl_add_u64 v[78:79], s[90:91], 0, v[78:79]
	v_lshl_add_u64 v[78:79], v[78:79], 0, v[154:155]
	s_waitcnt vmcnt(1)
	v_fmamk_f32 v76, v76, 0x3a000000, v189
	v_rsq_f32_e32 v76, v76
	s_nop 0
	v_pk_mul_f32 v[80:81], v[92:93], v[76:77] op_sel_hi:[1,0]
	v_pk_mul_f32 v[82:83], v[94:95], v[76:77] op_sel_hi:[1,0]
	s_waitcnt vmcnt(0)
	v_pk_mul_f32 v[72:73], v[72:73], v[80:81]
	v_pk_mul_f32 v[74:75], v[74:75], v[82:83]
	global_store_dwordx4 v[78:79], v[72:75], off
	global_load_dwordx4 v[72:75], v[148:149], off offset:16
	v_pk_mul_f32 v[80:81], v[84:85], v[76:77] op_sel_hi:[1,0]
	v_pk_mul_f32 v[82:83], v[86:87], v[76:77] op_sel_hi:[1,0]
	v_pk_mul_f32 v[68:69], v[68:69], v[76:77] op_sel_hi:[1,0]
	v_pk_mul_f32 v[70:71], v[70:71], v[76:77] op_sel_hi:[1,0]
	v_pk_mul_f32 v[64:65], v[64:65], v[76:77] op_sel_hi:[1,0]
	v_pk_mul_f32 v[66:67], v[66:67], v[76:77] op_sel_hi:[1,0]
	s_waitcnt vmcnt(0)
	v_pk_mul_f32 v[74:75], v[74:75], v[82:83]
	v_pk_mul_f32 v[72:73], v[72:73], v[80:81]
	global_store_dwordx4 v[78:79], v[72:75], off offset:16
	global_load_dwordx4 v[72:75], v[148:149], off offset:512
	s_waitcnt vmcnt(0)
	v_pk_mul_f32 v[70:71], v[74:75], v[70:71]
	v_pk_mul_f32 v[68:69], v[72:73], v[68:69]
	global_store_dwordx4 v[78:79], v[68:71], off offset:512
	global_load_dwordx4 v[68:71], v[148:149], off offset:528
	s_waitcnt vmcnt(0)
	v_pk_mul_f32 v[66:67], v[66:67], v[70:71]
	v_pk_mul_f32 v[64:65], v[64:65], v[68:69]
	global_store_dwordx4 v[78:79], v[64:67], off offset:528
	global_load_dword v68, v[144:145], off offset:512 sc1
	s_nop 0
	global_load_dwordx4 v[64:67], v[148:149], off
	v_lshlrev_b64 v[70:71], 13, v[164:165]
	v_lshl_add_u64 v[70:71], s[90:91], 0, v[70:71]
	v_lshl_add_u64 v[70:71], v[70:71], 0, v[154:155]
	s_waitcnt vmcnt(1)
	v_fmamk_f32 v68, v68, 0x3a000000, v189
	v_rsq_f32_e32 v68, v68
	s_nop 0
	v_pk_mul_f32 v[60:61], v[60:61], v[68:69] op_sel_hi:[1,0]
	v_pk_mul_f32 v[62:63], v[62:63], v[68:69] op_sel_hi:[1,0]
	s_waitcnt vmcnt(0)
	v_pk_mul_f32 v[60:61], v[64:65], v[60:61]
	v_pk_mul_f32 v[62:63], v[66:67], v[62:63]
	global_store_dwordx4 v[70:71], v[60:63], off
	global_load_dwordx4 v[60:63], v[148:149], off offset:16
	v_pk_mul_f32 v[56:57], v[56:57], v[68:69] op_sel_hi:[1,0]
	v_pk_mul_f32 v[58:59], v[58:59], v[68:69] op_sel_hi:[1,0]
	v_pk_mul_f32 v[52:53], v[52:53], v[68:69] op_sel_hi:[1,0]
	v_pk_mul_f32 v[54:55], v[54:55], v[68:69] op_sel_hi:[1,0]
	v_pk_mul_f32 v[48:49], v[48:49], v[68:69] op_sel_hi:[1,0]
	v_pk_mul_f32 v[50:51], v[50:51], v[68:69] op_sel_hi:[1,0]
	s_waitcnt vmcnt(0)
	v_pk_mul_f32 v[58:59], v[62:63], v[58:59]
	v_pk_mul_f32 v[56:57], v[60:61], v[56:57]
	global_store_dwordx4 v[70:71], v[56:59], off offset:16
	global_load_dwordx4 v[56:59], v[148:149], off offset:512
	s_waitcnt vmcnt(0)
	v_pk_mul_f32 v[54:55], v[58:59], v[54:55]
	v_pk_mul_f32 v[52:53], v[56:57], v[52:53]
	global_store_dwordx4 v[70:71], v[52:55], off offset:512
	global_load_dwordx4 v[52:55], v[148:149], off offset:528
	s_waitcnt vmcnt(0)
	v_pk_mul_f32 v[50:51], v[50:51], v[54:55]
	v_pk_mul_f32 v[48:49], v[48:49], v[52:53]
	global_store_dwordx4 v[70:71], v[48:51], off offset:528
	global_load_dword v52, v[144:145], off offset:576 sc1
	s_nop 0
	global_load_dwordx4 v[48:51], v[148:149], off
	v_lshlrev_b64 v[54:55], 13, v[168:169]
	v_lshl_add_u64 v[54:55], s[90:91], 0, v[54:55]
	v_lshl_add_u64 v[54:55], v[54:55], 0, v[154:155]
	s_waitcnt vmcnt(1)
	v_fmamk_f32 v52, v52, 0x3a000000, v189
	v_rsq_f32_e32 v52, v52
	s_nop 0
	v_pk_mul_f32 v[44:45], v[44:45], v[52:53] op_sel_hi:[1,0]
	v_pk_mul_f32 v[46:47], v[46:47], v[52:53] op_sel_hi:[1,0]
	s_waitcnt vmcnt(0)
	v_pk_mul_f32 v[44:45], v[48:49], v[44:45]
	v_pk_mul_f32 v[46:47], v[50:51], v[46:47]
	global_store_dwordx4 v[54:55], v[44:47], off
	global_load_dwordx4 v[44:47], v[148:149], off offset:16
	v_pk_mul_f32 v[40:41], v[40:41], v[52:53] op_sel_hi:[1,0]
	v_pk_mul_f32 v[42:43], v[42:43], v[52:53] op_sel_hi:[1,0]
	v_pk_mul_f32 v[36:37], v[36:37], v[52:53] op_sel_hi:[1,0]
	v_pk_mul_f32 v[38:39], v[38:39], v[52:53] op_sel_hi:[1,0]
	v_pk_mul_f32 v[32:33], v[32:33], v[52:53] op_sel_hi:[1,0]
	v_pk_mul_f32 v[34:35], v[34:35], v[52:53] op_sel_hi:[1,0]
	s_waitcnt vmcnt(0)
	v_pk_mul_f32 v[42:43], v[46:47], v[42:43]
	v_pk_mul_f32 v[40:41], v[44:45], v[40:41]
	global_store_dwordx4 v[54:55], v[40:43], off offset:16
	global_load_dwordx4 v[40:43], v[148:149], off offset:512
	s_waitcnt vmcnt(0)
	v_pk_mul_f32 v[38:39], v[42:43], v[38:39]
	v_pk_mul_f32 v[36:37], v[40:41], v[36:37]
	global_store_dwordx4 v[54:55], v[36:39], off offset:512
	global_load_dwordx4 v[36:39], v[148:149], off offset:528
	s_waitcnt vmcnt(0)
	v_pk_mul_f32 v[34:35], v[34:35], v[38:39]
	v_pk_mul_f32 v[32:33], v[32:33], v[36:37]
	global_store_dwordx4 v[54:55], v[32:35], off offset:528
	global_load_dword v36, v[144:145], off offset:640 sc1
	s_nop 0
	global_load_dwordx4 v[32:35], v[148:149], off
	v_lshlrev_b64 v[38:39], 13, v[172:173]
	v_lshl_add_u64 v[38:39], s[90:91], 0, v[38:39]
	v_lshl_add_u64 v[38:39], v[38:39], 0, v[154:155]
	s_waitcnt vmcnt(1)
	v_fmamk_f32 v36, v36, 0x3a000000, v189
	v_rsq_f32_e32 v36, v36
	s_nop 0
	v_pk_mul_f32 v[28:29], v[28:29], v[36:37] op_sel_hi:[1,0]
	v_pk_mul_f32 v[30:31], v[30:31], v[36:37] op_sel_hi:[1,0]
	s_waitcnt vmcnt(0)
	v_pk_mul_f32 v[28:29], v[32:33], v[28:29]
	v_pk_mul_f32 v[30:31], v[34:35], v[30:31]
	global_store_dwordx4 v[38:39], v[28:31], off
	global_load_dwordx4 v[28:31], v[148:149], off offset:16
	v_pk_mul_f32 v[24:25], v[24:25], v[36:37] op_sel_hi:[1,0]
	v_pk_mul_f32 v[26:27], v[26:27], v[36:37] op_sel_hi:[1,0]
	v_pk_mul_f32 v[20:21], v[20:21], v[36:37] op_sel_hi:[1,0]
	v_pk_mul_f32 v[22:23], v[22:23], v[36:37] op_sel_hi:[1,0]
	v_pk_mul_f32 v[16:17], v[16:17], v[36:37] op_sel_hi:[1,0]
	v_pk_mul_f32 v[18:19], v[18:19], v[36:37] op_sel_hi:[1,0]
	s_waitcnt vmcnt(0)
	v_pk_mul_f32 v[26:27], v[30:31], v[26:27]
	v_pk_mul_f32 v[24:25], v[28:29], v[24:25]
	global_store_dwordx4 v[38:39], v[24:27], off offset:16
	global_load_dwordx4 v[24:27], v[148:149], off offset:512
	s_waitcnt vmcnt(0)
	v_pk_mul_f32 v[22:23], v[26:27], v[22:23]
	v_pk_mul_f32 v[20:21], v[24:25], v[20:21]
	global_store_dwordx4 v[38:39], v[20:23], off offset:512
	global_load_dwordx4 v[20:23], v[148:149], off offset:528
	s_waitcnt vmcnt(0)
	v_pk_mul_f32 v[18:19], v[18:19], v[22:23]
	v_pk_mul_f32 v[16:17], v[16:17], v[20:21]
	global_store_dwordx4 v[38:39], v[16:19], off offset:528
	global_load_dword v20, v[144:145], off offset:704 sc1
	s_nop 0
	global_load_dwordx4 v[16:19], v[148:149], off
	v_lshlrev_b64 v[22:23], 13, v[174:175]
	v_lshl_add_u64 v[22:23], s[90:91], 0, v[22:23]
	v_lshl_add_u64 v[22:23], v[22:23], 0, v[154:155]
	s_waitcnt vmcnt(1)
	v_fmamk_f32 v20, v20, 0x3a000000, v189
	v_rsq_f32_e32 v20, v20
	s_nop 0
	v_pk_mul_f32 v[12:13], v[12:13], v[20:21] op_sel_hi:[1,0]
	v_pk_mul_f32 v[14:15], v[14:15], v[20:21] op_sel_hi:[1,0]
	s_waitcnt vmcnt(0)
	v_pk_mul_f32 v[12:13], v[16:17], v[12:13]
	v_pk_mul_f32 v[14:15], v[18:19], v[14:15]
	global_store_dwordx4 v[22:23], v[12:15], off
	global_load_dwordx4 v[12:15], v[148:149], off offset:16
	v_pk_mul_f32 v[8:9], v[8:9], v[20:21] op_sel_hi:[1,0]
	v_pk_mul_f32 v[10:11], v[10:11], v[20:21] op_sel_hi:[1,0]
	v_pk_mul_f32 v[4:5], v[4:5], v[20:21] op_sel_hi:[1,0]
	v_pk_mul_f32 v[6:7], v[6:7], v[20:21] op_sel_hi:[1,0]
	v_pk_mul_f32 v[0:1], v[0:1], v[20:21] op_sel_hi:[1,0]
	v_pk_mul_f32 v[2:3], v[2:3], v[20:21] op_sel_hi:[1,0]
	s_waitcnt vmcnt(0)
	v_pk_mul_f32 v[10:11], v[14:15], v[10:11]
	v_pk_mul_f32 v[8:9], v[12:13], v[8:9]
	global_store_dwordx4 v[22:23], v[8:11], off offset:16
	global_load_dwordx4 v[8:11], v[148:149], off offset:512
	s_waitcnt vmcnt(0)
	v_pk_mul_f32 v[6:7], v[10:11], v[6:7]
	v_pk_mul_f32 v[4:5], v[8:9], v[4:5]
	global_store_dwordx4 v[22:23], v[4:7], off offset:512
	global_load_dwordx4 v[4:7], v[148:149], off offset:528
	s_waitcnt vmcnt(0)
	v_pk_mul_f32 v[2:3], v[2:3], v[6:7]
	v_pk_mul_f32 v[0:1], v[0:1], v[4:5]
	global_store_dwordx4 v[22:23], v[0:3], off offset:528
.Lp7_epi_tail:
	s_and_b64 vcc, exec, s[44:45]
	s_mov_b64 s[22:23], -1
	s_cbranch_vccnz .LBB0_928
.LBB0_1034:
	s_andn2_b64 vcc, exec, s[4:5]
	s_cbranch_vccnz .LBB0_927
	s_barrier
	s_branch .LBB0_927
